# P0 w_in transposition rewritten with LDS-DMA double-buffered tiles (direct HBM to LDS strategy)
# baseline (speedup 1.0000x reference)
.LBB0_133:
	s_load_dwordx2 s[44:45], s[0:1], 0x10
	s_add_u32 s46, s58, 0x17800000
	s_addc_u32 s47, s59, 0
	s_add_u32 s48, s58, 0x6ac00000
	s_addc_u32 s49, s59, 0
	s_lshl_b32 s50, s76, 14
	v_mbcnt_lo_u32_b32 v70, -1, 0
	v_mbcnt_hi_u32_b32 v70, -1, v70
	v_lshrrev_b32_e32 v71, 3, v70
	v_and_b32_e32 v72, 7, v70
	v_mul_u32_u24_e32 v73, 0x1d000, v71
	v_xor_b32_e32 v74, 0, v72
	v_lshl_add_u32 v80, v74, 4, v73
	v_xor_b32_e32 v74, 1, v72
	v_lshl_add_u32 v81, v74, 4, v73
	v_add_u32_e32 v81, 0xe8000, v81
	v_xor_b32_e32 v74, 2, v72
	v_lshl_add_u32 v82, v74, 4, v73
	v_add_u32_e32 v82, 0x1d0000, v82
	v_xor_b32_e32 v74, 3, v72
	v_lshl_add_u32 v83, v74, 4, v73
	v_add_u32_e32 v83, 0x2b8000, v83
	v_xor_b32_e32 v74, 4, v72
	v_lshl_add_u32 v84, v74, 4, v73
	v_add_u32_e32 v84, 0x3a0000, v84
	v_xor_b32_e32 v74, 5, v72
	v_lshl_add_u32 v85, v74, 4, v73
	v_add_u32_e32 v85, 0x488000, v85
	v_xor_b32_e32 v74, 6, v72
	v_lshl_add_u32 v86, v74, 4, v73
	v_add_u32_e32 v86, 0x570000, v86
	v_xor_b32_e32 v74, 7, v72
	v_lshl_add_u32 v87, v74, 4, v73
	v_add_u32_e32 v87, 0x658000, v87
	v_lshlrev_b32_e32 v75, 10, v72
	v_lshrrev_b32_e32 v76, 5, v70
	v_and_b32_e32 v77, 3, v71
	v_lshlrev_b32_e32 v77, 2, v77
	v_add3_u32 v75, v75, v77, s50
	v_add_u32_e32 v74, 0, v76
	v_xor_b32_e32 v74, v74, v72
	v_lshl_add_u32 v88, v74, 4, v75
	v_add_u32_e32 v74, 2, v76
	v_xor_b32_e32 v74, v74, v72
	v_lshl_add_u32 v89, v74, 4, v75
	v_add_u32_e32 v74, 4, v76
	v_xor_b32_e32 v74, v74, v72
	v_lshl_add_u32 v90, v74, 4, v75
	v_add_u32_e32 v74, 6, v76
	v_xor_b32_e32 v74, v74, v72
	v_lshl_add_u32 v91, v74, 4, v75
	v_lshlrev_b32_e32 v92, 13, v71
	v_lshl_add_u32 v93, v72, 3, v92
	v_lshl_add_u32 v92, v72, 4, v92
	v_lshlrev_b32_e32 v94, 12, v71
	v_lshl_add_u32 v94, v72, 3, v94
	s_waitcnt lgkmcnt(0)
	s_mov_b32 s52, s2
	s_mov_b32 s53, 0
	s_mul_hi_i32 s4, s52, 0x8d3dcb09
	s_add_i32 s4, s4, s52
	s_lshr_b32 s5, s4, 31
	s_ashr_i32 s6, s4, 9
	s_add_i32 s6, s6, s5
	s_mul_i32 s4, s6, 0xfffffc60
	s_add_i32 s8, s52, s4
	s_mul_i32 s4, s6, 0x740000
	s_lshl_b32 s5, s8, 7
	s_add_u32 s4, s4, s5
	s_add_u32 s10, s44, s4
	s_addc_u32 s11, s45, 0
	s_add_i32 s9, s50, s53
	s_mov_b32 m0, s9
	s_nop 0
	global_load_lds_dwordx4 v80, s[10:11] nt
	s_add_i32 m0, s9, 0x400
	s_nop 0
	global_load_lds_dwordx4 v81, s[10:11] nt
	s_add_i32 m0, s9, 0x800
	s_nop 0
	global_load_lds_dwordx4 v82, s[10:11] nt
	s_add_i32 m0, s9, 0xc00
	s_nop 0
	global_load_lds_dwordx4 v83, s[10:11] nt
	s_add_i32 m0, s9, 0x1000
	s_nop 0
	global_load_lds_dwordx4 v84, s[10:11] nt
	s_add_i32 m0, s9, 0x1400
	s_nop 0
	global_load_lds_dwordx4 v85, s[10:11] nt
	s_add_i32 m0, s9, 0x1800
	s_nop 0
	global_load_lds_dwordx4 v86, s[10:11] nt
	s_add_i32 m0, s9, 0x1c00
	s_nop 0
	global_load_lds_dwordx4 v87, s[10:11] nt
	s_add_i32 s52, s52, s3
	s_mov_b32 s53, 0x2000
	s_mul_hi_i32 s4, s52, 0x8d3dcb09
	s_add_i32 s4, s4, s52
	s_lshr_b32 s5, s4, 31
	s_ashr_i32 s6, s4, 9
	s_add_i32 s6, s6, s5
	s_mul_i32 s4, s6, 0xfffffc60
	s_add_i32 s8, s52, s4
	s_mul_i32 s4, s6, 0x740000
	s_lshl_b32 s5, s8, 7
	s_add_u32 s4, s4, s5
	s_add_u32 s10, s44, s4
	s_addc_u32 s11, s45, 0
	s_add_i32 s9, s50, s53
	s_mov_b32 m0, s9
	s_nop 0
	global_load_lds_dwordx4 v80, s[10:11] nt
	s_add_i32 m0, s9, 0x400
	s_nop 0
	global_load_lds_dwordx4 v81, s[10:11] nt
	s_add_i32 m0, s9, 0x800
	s_nop 0
	global_load_lds_dwordx4 v82, s[10:11] nt
	s_add_i32 m0, s9, 0xc00
	s_nop 0
	global_load_lds_dwordx4 v83, s[10:11] nt
	s_add_i32 m0, s9, 0x1000
	s_nop 0
	global_load_lds_dwordx4 v84, s[10:11] nt
	s_add_i32 m0, s9, 0x1400
	s_nop 0
	global_load_lds_dwordx4 v85, s[10:11] nt
	s_add_i32 m0, s9, 0x1800
	s_nop 0
	global_load_lds_dwordx4 v86, s[10:11] nt
	s_add_i32 m0, s9, 0x1c00
	s_nop 0
	global_load_lds_dwordx4 v87, s[10:11] nt
	s_add_i32 s52, s52, s3
	s_mov_b32 s53, 0
	s_waitcnt vmcnt(8)
.Lp0t_loop:
	s_sub_i32 s4, s52, s3
	s_cmp_lt_i32 s4, 0xe800
	s_cbranch_scc1 .Lp0t_w12
	s_waitcnt vmcnt(4)
	s_branch .Lp0t_go
.Lp0t_w12:
	s_waitcnt vmcnt(12)
.Lp0t_go:
	ds_read2_b32 v[100:101], v88 offset0:0 offset1:32
	ds_read2_b32 v[102:103], v88 offset0:64 offset1:96
	ds_read2_b32 v[104:105], v88 offset0:128 offset1:160
	ds_read2_b32 v[106:107], v88 offset0:192 offset1:224
	ds_read2_b32 v[108:109], v89 offset0:0 offset1:32
	ds_read2_b32 v[110:111], v89 offset0:64 offset1:96
	ds_read2_b32 v[112:113], v89 offset0:128 offset1:160
	ds_read2_b32 v[114:115], v89 offset0:192 offset1:224
	ds_read2_b32 v[116:117], v90 offset0:0 offset1:32
	ds_read2_b32 v[118:119], v90 offset0:64 offset1:96
	ds_read2_b32 v[120:121], v90 offset0:128 offset1:160
	ds_read2_b32 v[122:123], v90 offset0:192 offset1:224
	ds_read2_b32 v[124:125], v91 offset0:0 offset1:32
	ds_read2_b32 v[126:127], v91 offset0:64 offset1:96
	ds_read2_b32 v[128:129], v91 offset0:128 offset1:160
	ds_read2_b32 v[130:131], v91 offset0:192 offset1:224
	s_mul_hi_i32 s4, s2, 0x8d3dcb09
	s_add_i32 s4, s4, s2
	s_lshr_b32 s5, s4, 31
	s_ashr_i32 s6, s4, 9
	s_add_i32 s6, s6, s5
	s_mul_i32 s4, s6, 0xfffffc60
	s_add_i32 s8, s2, s4
	s_waitcnt lgkmcnt(0)
	v_xor_b32_e32 v88, 0x2000, v88
	v_xor_b32_e32 v89, 0x2000, v89
	v_xor_b32_e32 v90, 0x2000, v90
	v_xor_b32_e32 v91, 0x2000, v91
	s_cmpk_lt_i32 s8, 0x120
	s_cbranch_scc1 .Lp0t_m3
	s_cmpk_gt_i32 s8, 0x29f
	s_cbranch_scc1 .Lp0t_m4
	s_lshl_b32 s4, s8, 18
	s_lshl_b32 s5, s6, 7
	s_add_u32 s4, s4, s5
	s_add_u32 s4, s46, s4
	s_addc_u32 s5, s47, 0
	v_cvt_pk_bf16_f32 v132, v100, v101
	v_cvt_pk_bf16_f32 v133, v102, v103
	v_cvt_pk_bf16_f32 v134, v104, v105
	v_cvt_pk_bf16_f32 v135, v106, v107
	global_store_dwordx4 v92, v[132:135], s[4:5] nt
	s_add_u32 s4, s4, 0x10000
	s_addc_u32 s5, s5, 0
	s_nop 1
	v_cvt_pk_bf16_f32 v132, v108, v109
	v_cvt_pk_bf16_f32 v133, v110, v111
	v_cvt_pk_bf16_f32 v134, v112, v113
	v_cvt_pk_bf16_f32 v135, v114, v115
	global_store_dwordx4 v92, v[132:135], s[4:5] nt
	s_add_u32 s4, s4, 0x10000
	s_addc_u32 s5, s5, 0
	s_nop 1
	v_cvt_pk_bf16_f32 v132, v116, v117
	v_cvt_pk_bf16_f32 v133, v118, v119
	v_cvt_pk_bf16_f32 v134, v120, v121
	v_cvt_pk_bf16_f32 v135, v122, v123
	global_store_dwordx4 v92, v[132:135], s[4:5] nt
	s_add_u32 s4, s4, 0x10000
	s_addc_u32 s5, s5, 0
	s_nop 1
	v_cvt_pk_bf16_f32 v132, v124, v125
	v_cvt_pk_bf16_f32 v133, v126, v127
	v_cvt_pk_bf16_f32 v134, v128, v129
	v_cvt_pk_bf16_f32 v135, v130, v131
	global_store_dwordx4 v92, v[132:135], s[4:5] nt
	s_branch .Lp0t_stored
.Lp0t_m3:
	s_lshl_b32 s4, s8, 18
	s_lshl_b32 s5, s6, 6
	s_add_u32 s4, s4, s5
	s_add_u32 s4, s46, s4
	s_addc_u32 s5, s47, 0
	v_mul_f32_e32 v100, 0x42800000, v100
	v_mul_f32_e32 v101, 0x42800000, v101
	v_mul_f32_e32 v102, 0x42800000, v102
	v_mul_f32_e32 v103, 0x42800000, v103
	v_mul_f32_e32 v104, 0x42800000, v104
	v_mul_f32_e32 v105, 0x42800000, v105
	v_mul_f32_e32 v106, 0x42800000, v106
	v_mul_f32_e32 v107, 0x42800000, v107
	v_mov_b32_e32 v132, 0
	v_mov_b32_e32 v133, 0
	v_cvt_pk_fp8_f32 v132, v100, v101
	v_cvt_pk_fp8_f32 v133, v104, v105
	v_cvt_pk_fp8_f32 v132, v102, v103 op_sel:[0,0,1]
	v_cvt_pk_fp8_f32 v133, v106, v107 op_sel:[0,0,1]
	global_store_dwordx2 v93, v[132:133], s[4:5] nt
	s_add_u32 s4, s4, 0x10000
	s_addc_u32 s5, s5, 0
	s_nop 1
	v_mul_f32_e32 v108, 0x42800000, v108
	v_mul_f32_e32 v109, 0x42800000, v109
	v_mul_f32_e32 v110, 0x42800000, v110
	v_mul_f32_e32 v111, 0x42800000, v111
	v_mul_f32_e32 v112, 0x42800000, v112
	v_mul_f32_e32 v113, 0x42800000, v113
	v_mul_f32_e32 v114, 0x42800000, v114
	v_mul_f32_e32 v115, 0x42800000, v115
	v_mov_b32_e32 v132, 0
	v_mov_b32_e32 v133, 0
	v_cvt_pk_fp8_f32 v132, v108, v109
	v_cvt_pk_fp8_f32 v133, v112, v113
	v_cvt_pk_fp8_f32 v132, v110, v111 op_sel:[0,0,1]
	v_cvt_pk_fp8_f32 v133, v114, v115 op_sel:[0,0,1]
	global_store_dwordx2 v93, v[132:133], s[4:5] nt
	s_add_u32 s4, s4, 0x10000
	s_addc_u32 s5, s5, 0
	s_nop 1
	v_mul_f32_e32 v116, 0x42800000, v116
	v_mul_f32_e32 v117, 0x42800000, v117
	v_mul_f32_e32 v118, 0x42800000, v118
	v_mul_f32_e32 v119, 0x42800000, v119
	v_mul_f32_e32 v120, 0x42800000, v120
	v_mul_f32_e32 v121, 0x42800000, v121
	v_mul_f32_e32 v122, 0x42800000, v122
	v_mul_f32_e32 v123, 0x42800000, v123
	v_mov_b32_e32 v132, 0
	v_mov_b32_e32 v133, 0
	v_cvt_pk_fp8_f32 v132, v116, v117
	v_cvt_pk_fp8_f32 v133, v120, v121
	v_cvt_pk_fp8_f32 v132, v118, v119 op_sel:[0,0,1]
	v_cvt_pk_fp8_f32 v133, v122, v123 op_sel:[0,0,1]
	global_store_dwordx2 v93, v[132:133], s[4:5] nt
	s_add_u32 s4, s4, 0x10000
	s_addc_u32 s5, s5, 0
	s_nop 1
	v_mul_f32_e32 v124, 0x42800000, v124
	v_mul_f32_e32 v125, 0x42800000, v125
	v_mul_f32_e32 v126, 0x42800000, v126
	v_mul_f32_e32 v127, 0x42800000, v127
	v_mul_f32_e32 v128, 0x42800000, v128
	v_mul_f32_e32 v129, 0x42800000, v129
	v_mul_f32_e32 v130, 0x42800000, v130
	v_mul_f32_e32 v131, 0x42800000, v131
	v_mov_b32_e32 v132, 0
	v_mov_b32_e32 v133, 0
	v_cvt_pk_fp8_f32 v132, v124, v125
	v_cvt_pk_fp8_f32 v133, v128, v129
	v_cvt_pk_fp8_f32 v132, v126, v127 op_sel:[0,0,1]
	v_cvt_pk_fp8_f32 v133, v130, v131 op_sel:[0,0,1]
	global_store_dwordx2 v93, v[132:133], s[4:5] nt
	s_branch .Lp0t_stored
.Lp0t_m4:
	s_lshl_b32 s4, s8, 17
	s_lshl_b32 s5, s6, 6
	s_add_u32 s4, s4, s5
	s_add_u32 s4, s48, s4
	s_addc_u32 s5, s49, 0
	v_mul_f32_e32 v100, 0x42800000, v100
	v_mul_f32_e32 v101, 0x42800000, v101
	v_mul_f32_e32 v102, 0x42800000, v102
	v_mul_f32_e32 v103, 0x42800000, v103
	v_mul_f32_e32 v104, 0x42800000, v104
	v_mul_f32_e32 v105, 0x42800000, v105
	v_mul_f32_e32 v106, 0x42800000, v106
	v_mul_f32_e32 v107, 0x42800000, v107
	v_mov_b32_e32 v132, 0
	v_mov_b32_e32 v133, 0
	v_cvt_pk_fp8_f32 v132, v100, v101
	v_cvt_pk_fp8_f32 v133, v104, v105
	v_cvt_pk_fp8_f32 v132, v102, v103 op_sel:[0,0,1]
	v_cvt_pk_fp8_f32 v133, v106, v107 op_sel:[0,0,1]
	global_store_dwordx2 v94, v[132:133], s[4:5] nt
	s_add_u32 s4, s4, 0x8000
	s_addc_u32 s5, s5, 0
	s_nop 1
	v_mul_f32_e32 v108, 0x42800000, v108
	v_mul_f32_e32 v109, 0x42800000, v109
	v_mul_f32_e32 v110, 0x42800000, v110
	v_mul_f32_e32 v111, 0x42800000, v111
	v_mul_f32_e32 v112, 0x42800000, v112
	v_mul_f32_e32 v113, 0x42800000, v113
	v_mul_f32_e32 v114, 0x42800000, v114
	v_mul_f32_e32 v115, 0x42800000, v115
	v_mov_b32_e32 v132, 0
	v_mov_b32_e32 v133, 0
	v_cvt_pk_fp8_f32 v132, v108, v109
	v_cvt_pk_fp8_f32 v133, v112, v113
	v_cvt_pk_fp8_f32 v132, v110, v111 op_sel:[0,0,1]
	v_cvt_pk_fp8_f32 v133, v114, v115 op_sel:[0,0,1]
	global_store_dwordx2 v94, v[132:133], s[4:5] nt
	s_add_u32 s4, s4, 0x8000
	s_addc_u32 s5, s5, 0
	s_nop 1
	v_mul_f32_e32 v116, 0x42800000, v116
	v_mul_f32_e32 v117, 0x42800000, v117
	v_mul_f32_e32 v118, 0x42800000, v118
	v_mul_f32_e32 v119, 0x42800000, v119
	v_mul_f32_e32 v120, 0x42800000, v120
	v_mul_f32_e32 v121, 0x42800000, v121
	v_mul_f32_e32 v122, 0x42800000, v122
	v_mul_f32_e32 v123, 0x42800000, v123
	v_mov_b32_e32 v132, 0
	v_mov_b32_e32 v133, 0
	v_cvt_pk_fp8_f32 v132, v116, v117
	v_cvt_pk_fp8_f32 v133, v120, v121
	v_cvt_pk_fp8_f32 v132, v118, v119 op_sel:[0,0,1]
	v_cvt_pk_fp8_f32 v133, v122, v123 op_sel:[0,0,1]
	global_store_dwordx2 v94, v[132:133], s[4:5] nt
	s_add_u32 s4, s4, 0x8000
	s_addc_u32 s5, s5, 0
	s_nop 1
	v_mul_f32_e32 v124, 0x42800000, v124
	v_mul_f32_e32 v125, 0x42800000, v125
	v_mul_f32_e32 v126, 0x42800000, v126
	v_mul_f32_e32 v127, 0x42800000, v127
	v_mul_f32_e32 v128, 0x42800000, v128
	v_mul_f32_e32 v129, 0x42800000, v129
	v_mul_f32_e32 v130, 0x42800000, v130
	v_mul_f32_e32 v131, 0x42800000, v131
	v_mov_b32_e32 v132, 0
	v_mov_b32_e32 v133, 0
	v_cvt_pk_fp8_f32 v132, v124, v125
	v_cvt_pk_fp8_f32 v133, v128, v129
	v_cvt_pk_fp8_f32 v132, v126, v127 op_sel:[0,0,1]
	v_cvt_pk_fp8_f32 v133, v130, v131 op_sel:[0,0,1]
	global_store_dwordx2 v94, v[132:133], s[4:5] nt
.Lp0t_stored:
	s_cmp_lt_i32 s52, 0xe800
	s_cbranch_scc0 .Lp0t_noissue
	s_mul_hi_i32 s4, s52, 0x8d3dcb09
	s_add_i32 s4, s4, s52
	s_lshr_b32 s5, s4, 31
	s_ashr_i32 s6, s4, 9
	s_add_i32 s6, s6, s5
	s_mul_i32 s4, s6, 0xfffffc60
	s_add_i32 s8, s52, s4
	s_mul_i32 s4, s6, 0x740000
	s_lshl_b32 s5, s8, 7
	s_add_u32 s4, s4, s5
	s_add_u32 s10, s44, s4
	s_addc_u32 s11, s45, 0
	s_add_i32 s9, s50, s53
	s_mov_b32 m0, s9
	s_nop 0
	global_load_lds_dwordx4 v80, s[10:11] nt
	s_add_i32 m0, s9, 0x400
	s_nop 0
	global_load_lds_dwordx4 v81, s[10:11] nt
	s_add_i32 m0, s9, 0x800
	s_nop 0
	global_load_lds_dwordx4 v82, s[10:11] nt
	s_add_i32 m0, s9, 0xc00
	s_nop 0
	global_load_lds_dwordx4 v83, s[10:11] nt
	s_add_i32 m0, s9, 0x1000
	s_nop 0
	global_load_lds_dwordx4 v84, s[10:11] nt
	s_add_i32 m0, s9, 0x1400
	s_nop 0
	global_load_lds_dwordx4 v85, s[10:11] nt
	s_add_i32 m0, s9, 0x1800
	s_nop 0
	global_load_lds_dwordx4 v86, s[10:11] nt
	s_add_i32 m0, s9, 0x1c00
	s_nop 0
	global_load_lds_dwordx4 v87, s[10:11] nt
.Lp0t_noissue:
	s_add_i32 s52, s52, s3
	s_xor_b32 s53, s53, 0x2000
	s_add_i32 s2, s2, s3
	s_cmp_lt_i32 s2, 0xe800
	s_cbranch_scc1 .Lp0t_loop
	s_branch .LBB0_153
